# v27 + proj K-loop: wave-group priority alternates every K-step (waves 0-3 vs 4-7), reset at tile epilogue
# baseline (speedup 1.0000x reference)
.Lpf_skip_L0:
	s_sub_u32 s4, s4, s81
	s_subb_u32 s5, s5, 0
	s_sub_u32 s0, s0, s81
	s_subb_u32 s1, s1, 0
	s_add_u32 s27, s0, 0xc000
	s_addc_u32 s28, s1, 0
	s_add_u32 s29, s0, 0x8000
	s_addc_u32 s30, s1, 0
	s_add_u32 s31, s0, 0x4000
	s_addc_u32 s34, s1, 0
	s_add_u32 s35, s0, 0x0
	s_addc_u32 s36, s1, 0
	s_add_u32 s37, s4, 0xc000
	s_addc_u32 s39, s5, 0
	s_add_u32 s40, s4, 0x8000
	s_addc_u32 s42, s5, 0
	s_add_u32 s43, s4, 0x4000
	s_addc_u32 s44, s5, 0
	s_add_u32 s45, s4, 0x0
	s_addc_u32 s46, s5, 0
	s_mov_b64 s[0:1], 0
	s_mov_b32 s48, s17
	s_mov_b32 s47, s17
	v_mov_b32_e32 v0, v147
	v_mov_b32_e32 v1, v147
	v_mov_b32_e32 v2, v147
	v_mov_b32_e32 v3, v147
	v_mov_b32_e32 v4, v147
	v_mov_b32_e32 v5, v147
	v_mov_b32_e32 v6, v147
	v_mov_b32_e32 v7, v147
	v_mov_b32_e32 v8, v147
	v_mov_b32_e32 v9, v147
	v_mov_b32_e32 v10, v147
	v_mov_b32_e32 v11, v147
	v_mov_b32_e32 v12, v147
	v_mov_b32_e32 v13, v147
	v_mov_b32_e32 v14, v147
	v_mov_b32_e32 v15, v147
	v_mov_b32_e32 v16, v147
	v_mov_b32_e32 v17, v147
	v_mov_b32_e32 v18, v147
	v_mov_b32_e32 v19, v147
	v_mov_b32_e32 v20, v147
	v_mov_b32_e32 v21, v147
	v_mov_b32_e32 v22, v147
	v_mov_b32_e32 v23, v147
	v_mov_b32_e32 v24, v147
	v_mov_b32_e32 v25, v147
	v_mov_b32_e32 v26, v147
	v_mov_b32_e32 v27, v147
	v_mov_b32_e32 v28, v147
	v_mov_b32_e32 v29, v147
	v_mov_b32_e32 v30, v147
	v_mov_b32_e32 v31, v147
	v_mov_b32_e32 v32, v147
	v_mov_b32_e32 v33, v147
	v_mov_b32_e32 v34, v147
	v_mov_b32_e32 v35, v147
	v_mov_b32_e32 v36, v147
	v_mov_b32_e32 v37, v147
	v_mov_b32_e32 v38, v147
	v_mov_b32_e32 v39, v147
	v_mov_b32_e32 v40, v147
	v_mov_b32_e32 v41, v147
	v_mov_b32_e32 v42, v147
	v_mov_b32_e32 v43, v147
	v_mov_b32_e32 v44, v147
	v_mov_b32_e32 v45, v147
	v_mov_b32_e32 v46, v147
	v_mov_b32_e32 v47, v147
	v_mov_b32_e32 v48, v147
	v_mov_b32_e32 v49, v147
	v_mov_b32_e32 v50, v147
	v_mov_b32_e32 v51, v147
	v_mov_b32_e32 v52, v147
	v_mov_b32_e32 v53, v147
	v_mov_b32_e32 v54, v147
	v_mov_b32_e32 v55, v147
	v_mov_b32_e32 v56, v147
	v_mov_b32_e32 v57, v147
	v_mov_b32_e32 v58, v147
	v_mov_b32_e32 v59, v147
	v_mov_b32_e32 v60, v147
	v_mov_b32_e32 v61, v147
	v_mov_b32_e32 v62, v147
	v_mov_b32_e32 v63, v147
	v_mov_b32_e32 v64, v147
	v_mov_b32_e32 v65, v147
	v_mov_b32_e32 v66, v147
	v_mov_b32_e32 v67, v147
	v_mov_b32_e32 v68, v147
	v_mov_b32_e32 v69, v147
	v_mov_b32_e32 v70, v147
	v_mov_b32_e32 v71, v147
	v_mov_b32_e32 v72, v147
	v_mov_b32_e32 v73, v147
	v_mov_b32_e32 v74, v147
	v_mov_b32_e32 v75, v147
	v_mov_b32_e32 v76, v147
	v_mov_b32_e32 v77, v147
	v_mov_b32_e32 v78, v147
	v_mov_b32_e32 v79, v147
	v_mov_b32_e32 v80, v147
	v_mov_b32_e32 v81, v147
	v_mov_b32_e32 v82, v147
	v_mov_b32_e32 v83, v147
	v_mov_b32_e32 v84, v147
	v_mov_b32_e32 v85, v147
	v_mov_b32_e32 v86, v147
	v_mov_b32_e32 v87, v147
	v_mov_b32_e32 v88, v147
	v_mov_b32_e32 v89, v147
	v_mov_b32_e32 v90, v147
	v_mov_b32_e32 v91, v147
	v_mov_b32_e32 v92, v147
	v_mov_b32_e32 v93, v147
	v_mov_b32_e32 v94, v147
	v_mov_b32_e32 v95, v147
	v_mov_b32_e32 v96, v147
	v_mov_b32_e32 v97, v147
	v_mov_b32_e32 v98, v147
	v_mov_b32_e32 v99, v147
	v_mov_b32_e32 v100, v147
	v_mov_b32_e32 v101, v147
	v_mov_b32_e32 v102, v147
	v_mov_b32_e32 v103, v147
	v_mov_b32_e32 v104, v147
	v_mov_b32_e32 v105, v147
	v_mov_b32_e32 v106, v147
	v_mov_b32_e32 v107, v147
	v_mov_b32_e32 v108, v147
	v_mov_b32_e32 v109, v147
	v_mov_b32_e32 v110, v147
	v_mov_b32_e32 v111, v147
	v_mov_b32_e32 v112, v147
	v_mov_b32_e32 v113, v147
	v_mov_b32_e32 v114, v147
	v_mov_b32_e32 v115, v147
	v_mov_b32_e32 v116, v147
	v_mov_b32_e32 v117, v147
	v_mov_b32_e32 v118, v147
	v_mov_b32_e32 v119, v147
	v_mov_b32_e32 v120, v147
	v_mov_b32_e32 v121, v147
	v_mov_b32_e32 v122, v147
	v_mov_b32_e32 v123, v147
	v_mov_b32_e32 v124, v147
	v_mov_b32_e32 v125, v147
	v_mov_b32_e32 v126, v147
	v_mov_b32_e32 v127, v147
	v_cmp_gt_u32_e32 vcc, 0x100, v178
	s_mov_b32 s100, 0
	s_cbranch_vccnz .Lpa_L0
	s_mov_b32 s100, 1

.LBB0_130:
	s_xor_b32 s100, s100, 1
	s_cbranch_scc0 .Lpb_L0
	s_setprio 1
	s_branch .Lpc_L0
.Lpb_L0:
	s_setprio 0
.Lpc_L0:
	v_add_u32_e32 v164, v168, v189
	v_add_u32_e32 v169, v146, v189
	s_waitcnt lgkmcnt(2)
	v_mfma_f32_32x32x16_bf16 v[0:15], v[128:131], v[132:135], v[0:15]
	ds_read_b128 v[156:159], v164
	s_add_u32 s0, s0, 0x80
	s_addc_u32 s1, s1, 0
	s_add_i32 s47, s47, 1
	s_cmpk_lg_i32 s0, 0x800
	s_mov_b32 s48, s52
	v_mfma_f32_32x32x16_bf16 v[16:31], v[152:155], v[132:135], v[16:31]
	ds_read_b128 v[132:135], v164 offset:4096
	s_waitcnt lgkmcnt(4)
	v_mfma_f32_32x32x16_bf16 v[32:47], v[128:131], v[136:139], v[32:47]
	ds_read_b128 v[160:163], v164 offset:8192
	v_mfma_f32_32x32x16_bf16 v[48:63], v[152:155], v[136:139], v[48:63]
	ds_read_b128 v[136:139], v164 offset:12288
	s_waitcnt lgkmcnt(5)
	v_mfma_f32_32x32x16_bf16 v[64:79], v[128:131], v[140:143], v[64:79]
	ds_read_b128 v[164:167], v169 offset:32768
	v_mfma_f32_32x32x16_bf16 v[80:95], v[152:155], v[140:143], v[80:95]
	ds_read_b128 v[140:143], v169 offset:36864
	v_add_u32_e32 v169, v168, v190
	s_waitcnt lgkmcnt(6)
	v_mfma_f32_32x32x16_bf16 v[96:111], v[128:131], v[148:151], v[96:111]
	v_mfma_f32_32x32x16_bf16 v[112:127], v[152:155], v[148:151], v[112:127]
	s_waitcnt lgkmcnt(1)
	v_mfma_f32_32x32x16_bf16 v[0:15], v[164:167], v[156:159], v[0:15]
	ds_read_b128 v[128:131], v169
	s_waitcnt lgkmcnt(1)
	v_mfma_f32_32x32x16_bf16 v[16:31], v[140:143], v[156:159], v[16:31]
	ds_read_b128 v[148:151], v169 offset:4096
	v_mfma_f32_32x32x16_bf16 v[32:47], v[164:167], v[132:135], v[32:47]
	ds_read_b128 v[152:155], v169 offset:8192
	v_mfma_f32_32x32x16_bf16 v[48:63], v[140:143], v[132:135], v[48:63]
	ds_read_b128 v[132:135], v169 offset:12288
	v_add_u32_e32 v169, v146, v190
	v_add_u32_e32 v146, v146, v191
	v_mfma_f32_32x32x16_bf16 v[64:79], v[164:167], v[160:163], v[64:79]
	ds_read_b128 v[156:159], v169 offset:32768
	v_mfma_f32_32x32x16_bf16 v[80:95], v[140:143], v[160:163], v[80:95]
	ds_read_b128 v[160:163], v169 offset:36864
	v_mfma_f32_32x32x16_bf16 v[96:111], v[164:167], v[136:139], v[96:111]
	v_add_u32_e32 v164, v168, v191
	v_mfma_f32_32x32x16_bf16 v[112:127], v[140:143], v[136:139], v[112:127]
	s_waitcnt lgkmcnt(1)
	v_mfma_f32_32x32x16_bf16 v[0:15], v[156:159], v[128:131], v[0:15]
	ds_read_b128 v[136:139], v164
	s_waitcnt lgkmcnt(1)
	v_mfma_f32_32x32x16_bf16 v[16:31], v[160:163], v[128:131], v[16:31]
	ds_read_b128 v[128:131], v164 offset:4096
	v_mfma_f32_32x32x16_bf16 v[32:47], v[156:159], v[148:151], v[32:47]
	ds_read_b128 v[140:143], v164 offset:8192
	v_mfma_f32_32x32x16_bf16 v[48:63], v[160:163], v[148:151], v[48:63]
	ds_read_b128 v[148:151], v164 offset:12288
	v_mfma_f32_32x32x16_bf16 v[64:79], v[156:159], v[152:155], v[64:79]
	ds_read_b128 v[164:167], v146 offset:32768
	v_mfma_f32_32x32x16_bf16 v[80:95], v[160:163], v[152:155], v[80:95]
	ds_read_b128 v[152:155], v146 offset:36864
	v_mfma_f32_32x32x16_bf16 v[96:111], v[156:159], v[132:135], v[96:111]
	v_mfma_f32_32x32x16_bf16 v[112:127], v[160:163], v[132:135], v[112:127]
	s_waitcnt lgkmcnt(0)
	s_cbranch_scc0 .Lxt_L0
	s_waitcnt vmcnt(0)
	s_barrier
	s_and_b32 s4, s48, 0x10000
	v_or_b32_e32 v146, s4, v187
	v_add_u32_e32 v194, v146, v188
	v_add_u32_e32 v168, s4, v186
	v_add_u32_e32 v195, v168, v188
	ds_read_b128 v[132:135], v195
	v_mfma_f32_32x32x16_bf16 v[16:31], v[152:155], v[136:139], v[16:31]
	v_mfma_f32_32x32x16_bf16 v[48:63], v[152:155], v[128:131], v[48:63]
	v_mfma_f32_32x32x16_bf16 v[80:95], v[152:155], v[140:143], v[80:95]
	v_mfma_f32_32x32x16_bf16 v[112:127], v[152:155], v[148:151], v[112:127]
	ds_read_b128 v[152:155], v194 offset:36864
	v_mfma_f32_32x32x16_bf16 v[0:15], v[164:167], v[136:139], v[0:15]
	ds_read_b128 v[136:139], v195 offset:4096
	v_mfma_f32_32x32x16_bf16 v[32:47], v[164:167], v[128:131], v[32:47]
	ds_read_b128 v[128:131], v194 offset:32768
	v_mfma_f32_32x32x16_bf16 v[64:79], v[164:167], v[140:143], v[64:79]
	ds_read_b128 v[140:143], v195 offset:8192
	v_mfma_f32_32x32x16_bf16 v[96:111], v[164:167], v[148:151], v[96:111]
	ds_read_b128 v[148:151], v195 offset:12288
	s_cmp_lt_u32 s47, 15
	s_mov_b64 s[4:5], -1
	s_cbranch_scc1 .Lft_L0_133
	s_add_i32 s52, s48, 0x10000
	s_mov_b64 s[4:5], 0

.Lpf_skip_L1:
	s_sub_u32 s6, s6, s81
	s_subb_u32 s7, s7, 0
	s_sub_u32 s4, s4, s81
	s_subb_u32 s5, s5, 0
	s_add_u32 s27, s4, 0xc000
	s_addc_u32 s28, s5, 0
	s_add_u32 s29, s4, 0x8000
	s_addc_u32 s30, s5, 0
	s_add_u32 s31, s4, 0x4000
	s_addc_u32 s34, s5, 0
	s_add_u32 s35, s4, 0x0
	s_addc_u32 s36, s5, 0
	s_add_u32 s37, s6, 0xc000
	s_addc_u32 s38, s7, 0
	s_add_u32 s39, s6, 0x8000
	s_addc_u32 s40, s7, 0
	s_add_u32 s41, s6, 0x4000
	s_addc_u32 s42, s7, 0
	s_add_u32 s43, s6, 0x0
	s_addc_u32 s44, s7, 0
	s_mov_b64 s[4:5], 0
	s_mov_b32 s46, s17
	s_mov_b32 s45, s17
	v_mov_b32_e32 v0, v145
	v_mov_b32_e32 v1, v145
	v_mov_b32_e32 v2, v145
	v_mov_b32_e32 v3, v145
	v_mov_b32_e32 v4, v145
	v_mov_b32_e32 v5, v145
	v_mov_b32_e32 v6, v145
	v_mov_b32_e32 v7, v145
	v_mov_b32_e32 v8, v145
	v_mov_b32_e32 v9, v145
	v_mov_b32_e32 v10, v145
	v_mov_b32_e32 v11, v145
	v_mov_b32_e32 v12, v145
	v_mov_b32_e32 v13, v145
	v_mov_b32_e32 v14, v145
	v_mov_b32_e32 v15, v145
	v_mov_b32_e32 v16, v145
	v_mov_b32_e32 v17, v145
	v_mov_b32_e32 v18, v145
	v_mov_b32_e32 v19, v145
	v_mov_b32_e32 v20, v145
	v_mov_b32_e32 v21, v145
	v_mov_b32_e32 v22, v145
	v_mov_b32_e32 v23, v145
	v_mov_b32_e32 v24, v145
	v_mov_b32_e32 v25, v145
	v_mov_b32_e32 v26, v145
	v_mov_b32_e32 v27, v145
	v_mov_b32_e32 v28, v145
	v_mov_b32_e32 v29, v145
	v_mov_b32_e32 v30, v145
	v_mov_b32_e32 v31, v145
	v_mov_b32_e32 v32, v145
	v_mov_b32_e32 v33, v145
	v_mov_b32_e32 v34, v145
	v_mov_b32_e32 v35, v145
	v_mov_b32_e32 v36, v145
	v_mov_b32_e32 v37, v145
	v_mov_b32_e32 v38, v145
	v_mov_b32_e32 v39, v145
	v_mov_b32_e32 v40, v145
	v_mov_b32_e32 v41, v145
	v_mov_b32_e32 v42, v145
	v_mov_b32_e32 v43, v145
	v_mov_b32_e32 v44, v145
	v_mov_b32_e32 v45, v145
	v_mov_b32_e32 v46, v145
	v_mov_b32_e32 v47, v145
	v_mov_b32_e32 v48, v145
	v_mov_b32_e32 v49, v145
	v_mov_b32_e32 v50, v145
	v_mov_b32_e32 v51, v145
	v_mov_b32_e32 v52, v145
	v_mov_b32_e32 v53, v145
	v_mov_b32_e32 v54, v145
	v_mov_b32_e32 v55, v145
	v_mov_b32_e32 v56, v145
	v_mov_b32_e32 v57, v145
	v_mov_b32_e32 v58, v145
	v_mov_b32_e32 v59, v145
	v_mov_b32_e32 v60, v145
	v_mov_b32_e32 v61, v145
	v_mov_b32_e32 v62, v145
	v_mov_b32_e32 v63, v145
	v_mov_b32_e32 v64, v145
	v_mov_b32_e32 v65, v145
	v_mov_b32_e32 v66, v145
	v_mov_b32_e32 v67, v145
	v_mov_b32_e32 v68, v145
	v_mov_b32_e32 v69, v145
	v_mov_b32_e32 v70, v145
	v_mov_b32_e32 v71, v145
	v_mov_b32_e32 v72, v145
	v_mov_b32_e32 v73, v145
	v_mov_b32_e32 v74, v145
	v_mov_b32_e32 v75, v145
	v_mov_b32_e32 v76, v145
	v_mov_b32_e32 v77, v145
	v_mov_b32_e32 v78, v145
	v_mov_b32_e32 v79, v145
	v_mov_b32_e32 v80, v145
	v_mov_b32_e32 v81, v145
	v_mov_b32_e32 v82, v145
	v_mov_b32_e32 v83, v145
	v_mov_b32_e32 v84, v145
	v_mov_b32_e32 v85, v145
	v_mov_b32_e32 v86, v145
	v_mov_b32_e32 v87, v145
	v_mov_b32_e32 v88, v145
	v_mov_b32_e32 v89, v145
	v_mov_b32_e32 v90, v145
	v_mov_b32_e32 v91, v145
	v_mov_b32_e32 v92, v145
	v_mov_b32_e32 v93, v145
	v_mov_b32_e32 v94, v145
	v_mov_b32_e32 v95, v145
	v_mov_b32_e32 v96, v145
	v_mov_b32_e32 v97, v145
	v_mov_b32_e32 v98, v145
	v_mov_b32_e32 v99, v145
	v_mov_b32_e32 v100, v145
	v_mov_b32_e32 v101, v145
	v_mov_b32_e32 v102, v145
	v_mov_b32_e32 v103, v145
	v_mov_b32_e32 v104, v145
	v_mov_b32_e32 v105, v145
	v_mov_b32_e32 v106, v145
	v_mov_b32_e32 v107, v145
	v_mov_b32_e32 v108, v145
	v_mov_b32_e32 v109, v145
	v_mov_b32_e32 v110, v145
	v_mov_b32_e32 v111, v145
	v_mov_b32_e32 v112, v145
	v_mov_b32_e32 v113, v145
	v_mov_b32_e32 v114, v145
	v_mov_b32_e32 v115, v145
	v_mov_b32_e32 v116, v145
	v_mov_b32_e32 v117, v145
	v_mov_b32_e32 v118, v145
	v_mov_b32_e32 v119, v145
	v_mov_b32_e32 v120, v145
	v_mov_b32_e32 v121, v145
	v_mov_b32_e32 v122, v145
	v_mov_b32_e32 v123, v145
	v_mov_b32_e32 v124, v145
	v_mov_b32_e32 v125, v145
	v_mov_b32_e32 v126, v145
	v_mov_b32_e32 v127, v145
	v_cmp_gt_u32_e32 vcc, 0x100, v178
	s_mov_b32 s100, 0
	s_cbranch_vccnz .Lpa_L1
	s_mov_b32 s100, 1

.Lpb_L1:
	s_setprio 0
.Lpc_L1:
	v_add_u32_e32 v162, v166, v189
	v_add_u32_e32 v167, v144, v189
	s_waitcnt lgkmcnt(2)
	v_mfma_f32_32x32x16_bf16 v[0:15], v[128:131], v[132:135], v[0:15]
	ds_read_b128 v[154:157], v162
	s_add_u32 s4, s4, 0x80
	s_addc_u32 s5, s5, 0
	s_add_i32 s45, s45, 1
	s_cmpk_lg_i32 s4, 0x800
	s_mov_b32 s46, s50
	v_mfma_f32_32x32x16_bf16 v[16:31], v[150:153], v[132:135], v[16:31]
	ds_read_b128 v[132:135], v162 offset:4096
	s_waitcnt lgkmcnt(4)
	v_mfma_f32_32x32x16_bf16 v[32:47], v[128:131], v[136:139], v[32:47]
	ds_read_b128 v[158:161], v162 offset:8192
	v_mfma_f32_32x32x16_bf16 v[48:63], v[150:153], v[136:139], v[48:63]
	ds_read_b128 v[136:139], v162 offset:12288
	s_waitcnt lgkmcnt(5)
	v_mfma_f32_32x32x16_bf16 v[64:79], v[128:131], v[140:143], v[64:79]
	ds_read_b128 v[162:165], v167 offset:32768
	v_mfma_f32_32x32x16_bf16 v[80:95], v[150:153], v[140:143], v[80:95]
	ds_read_b128 v[140:143], v167 offset:36864
	v_add_u32_e32 v167, v166, v190
	s_waitcnt lgkmcnt(6)
	v_mfma_f32_32x32x16_bf16 v[96:111], v[128:131], v[146:149], v[96:111]
	v_mfma_f32_32x32x16_bf16 v[112:127], v[150:153], v[146:149], v[112:127]
	s_waitcnt lgkmcnt(1)
	v_mfma_f32_32x32x16_bf16 v[0:15], v[162:165], v[154:157], v[0:15]
	ds_read_b128 v[128:131], v167
	s_waitcnt lgkmcnt(1)
	v_mfma_f32_32x32x16_bf16 v[16:31], v[140:143], v[154:157], v[16:31]
	ds_read_b128 v[146:149], v167 offset:4096
	v_mfma_f32_32x32x16_bf16 v[32:47], v[162:165], v[132:135], v[32:47]
	ds_read_b128 v[150:153], v167 offset:8192
	v_mfma_f32_32x32x16_bf16 v[48:63], v[140:143], v[132:135], v[48:63]
	ds_read_b128 v[132:135], v167 offset:12288
	v_add_u32_e32 v167, v144, v190
	v_add_u32_e32 v144, v144, v191
	v_mfma_f32_32x32x16_bf16 v[64:79], v[162:165], v[158:161], v[64:79]
	ds_read_b128 v[154:157], v167 offset:32768
	v_mfma_f32_32x32x16_bf16 v[80:95], v[140:143], v[158:161], v[80:95]
	ds_read_b128 v[158:161], v167 offset:36864
	v_mfma_f32_32x32x16_bf16 v[96:111], v[162:165], v[136:139], v[96:111]
	v_add_u32_e32 v162, v166, v191
	v_mfma_f32_32x32x16_bf16 v[112:127], v[140:143], v[136:139], v[112:127]
	s_waitcnt lgkmcnt(1)
	v_mfma_f32_32x32x16_bf16 v[0:15], v[154:157], v[128:131], v[0:15]
	ds_read_b128 v[136:139], v162
	s_waitcnt lgkmcnt(1)
	v_mfma_f32_32x32x16_bf16 v[16:31], v[158:161], v[128:131], v[16:31]
	ds_read_b128 v[128:131], v162 offset:4096
	v_mfma_f32_32x32x16_bf16 v[32:47], v[154:157], v[146:149], v[32:47]
	ds_read_b128 v[140:143], v162 offset:8192
	v_mfma_f32_32x32x16_bf16 v[48:63], v[158:161], v[146:149], v[48:63]
	ds_read_b128 v[146:149], v162 offset:12288
	v_mfma_f32_32x32x16_bf16 v[64:79], v[154:157], v[150:153], v[64:79]
	ds_read_b128 v[162:165], v144 offset:32768
	v_mfma_f32_32x32x16_bf16 v[80:95], v[158:161], v[150:153], v[80:95]
	ds_read_b128 v[150:153], v144 offset:36864
	v_mfma_f32_32x32x16_bf16 v[96:111], v[154:157], v[132:135], v[96:111]
	v_mfma_f32_32x32x16_bf16 v[112:127], v[158:161], v[132:135], v[112:127]
	s_waitcnt lgkmcnt(0)
	s_cbranch_scc0 .Lxt_L1
	s_waitcnt vmcnt(0)
	s_barrier
	s_and_b32 s6, s46, 0x10000
	v_or_b32_e32 v144, s6, v187
	v_add_u32_e32 v194, v144, v188
	v_add_u32_e32 v166, s6, v186
	v_add_u32_e32 v195, v166, v188
	ds_read_b128 v[132:135], v195
	v_mfma_f32_32x32x16_bf16 v[16:31], v[150:153], v[136:139], v[16:31]
	v_mfma_f32_32x32x16_bf16 v[48:63], v[150:153], v[128:131], v[48:63]
	v_mfma_f32_32x32x16_bf16 v[80:95], v[150:153], v[140:143], v[80:95]
	v_mfma_f32_32x32x16_bf16 v[112:127], v[150:153], v[146:149], v[112:127]
	ds_read_b128 v[150:153], v194 offset:36864
	v_mfma_f32_32x32x16_bf16 v[0:15], v[162:165], v[136:139], v[0:15]
	ds_read_b128 v[136:139], v195 offset:4096
	v_mfma_f32_32x32x16_bf16 v[32:47], v[162:165], v[128:131], v[32:47]
	ds_read_b128 v[128:131], v194 offset:32768
	v_mfma_f32_32x32x16_bf16 v[64:79], v[162:165], v[140:143], v[64:79]
	ds_read_b128 v[140:143], v195 offset:8192
	v_mfma_f32_32x32x16_bf16 v[96:111], v[162:165], v[146:149], v[96:111]
	ds_read_b128 v[146:149], v195 offset:12288
	s_cmp_lt_u32 s45, 15
	s_mov_b64 s[6:7], -1
	s_cbranch_scc1 .Lft_L1_728
	s_add_i32 s50, s46, 0x10000
	s_mov_b64 s[6:7], 0
